# S5 pass-B recurrence: LDS reads of the four steps hoisted above the state stores (counted lgkmcnt) on top of the hand-scheduled attention loop
# speedup vs baseline: 1.0025x; 1.0025x over previous
.LBB0_499:
	v_add_u32_e32 v119, s1, v102
	v_add_u32_e32 v50, 0x10000, v119
	v_add_u32_e32 v132, 0x10210, v119
	v_add_u32_e32 v133, 0x10420, v119
	v_add_u32_e32 v134, 0x10630, v119
	ds_read_b64 v[124:125], v50
	ds_read_b64 v[126:127], v132
	ds_read_b64 v[128:129], v133
	ds_read_b64 v[130:131], v134
	s_waitcnt vmcnt(0)
	v_pk_mul_f32 v[48:49], v[70:71], v[68:69] op_sel:[0,1]
	v_add_u32_e32 v122, s1, v101
	v_pk_fma_f32 v[120:121], v[66:67], v[68:69], v[48:49] neg_lo:[0,0,1] neg_hi:[0,0,1]
	v_pk_fma_f32 v[48:49], v[66:67], v[68:69], v[48:49] op_sel_hi:[1,0,1]
	v_mov_b32_e32 v121, v49
	s_waitcnt lgkmcnt(3)
	v_pk_add_f32 v[48:49], v[120:121], v[124:125]
	v_add_u32_e32 v51, 0x10000, v122
	v_cvt_pk_bf16_f32 v50, v48, v49
	ds_write_b32 v51, v50
	v_pk_mul_f32 v[50:51], v[70:71], v[48:49] op_sel:[0,1]
	s_addk_i32 s1, 0x840
	v_pk_fma_f32 v[120:121], v[66:67], v[48:49], v[50:51] neg_lo:[0,0,1] neg_hi:[0,0,1]
	v_pk_fma_f32 v[48:49], v[66:67], v[48:49], v[50:51] op_sel_hi:[1,0,1]
	v_add_u32_e32 v51, 0x10210, v122
	v_mov_b32_e32 v121, v49
	s_waitcnt lgkmcnt(3)
	v_pk_add_f32 v[48:49], v[120:121], v[126:127]
	v_cvt_pk_bf16_f32 v50, v48, v49
	ds_write_b32 v51, v50
	v_pk_mul_f32 v[50:51], v[70:71], v[48:49] op_sel:[0,1]
	s_cmpk_eq_i32 s1, 0x2100
	v_pk_fma_f32 v[120:121], v[66:67], v[48:49], v[50:51] neg_lo:[0,0,1] neg_hi:[0,0,1]
	v_pk_fma_f32 v[48:49], v[66:67], v[48:49], v[50:51] op_sel_hi:[1,0,1]
	v_add_u32_e32 v51, 0x10420, v122
	v_mov_b32_e32 v121, v49
	s_waitcnt lgkmcnt(3)
	v_pk_add_f32 v[48:49], v[120:121], v[128:129]
	v_cvt_pk_bf16_f32 v50, v48, v49
	ds_write_b32 v51, v50
	v_pk_mul_f32 v[50:51], v[70:71], v[48:49] op_sel:[0,1]
	s_nop 0
	v_pk_fma_f32 v[120:121], v[66:67], v[48:49], v[50:51] neg_lo:[0,0,1] neg_hi:[0,0,1]
	v_pk_fma_f32 v[48:49], v[66:67], v[48:49], v[50:51] op_sel_hi:[1,0,1]
	s_nop 0
	v_mov_b32_e32 v121, v49
	s_waitcnt lgkmcnt(3)
	v_pk_add_f32 v[68:69], v[120:121], v[130:131]
	v_add_u32_e32 v49, 0x10630, v122
	v_cvt_pk_bf16_f32 v48, v68, v69
	ds_write_b32 v49, v48
	s_cbranch_scc0 .LBB0_499
	ds_read_b128 v[48:51], v105
	ds_read_b128 v[120:123], v105 offset:64
	v_lshl_add_u32 v119, s16, 14, v118
	s_add_i32 s16, s16, 1
	s_cmp_eq_u32 s16, 4
	s_waitcnt lgkmcnt(1)
	v_mfma_f32_16x16x32_bf16 v[48:51], v[48:51], v[32:35], 0
	s_waitcnt lgkmcnt(0)
	v_mfma_f32_16x16x32_bf16 v[48:51], v[120:123], v[36:39], v[48:51]
	ds_read_b128 v[120:123], v105 offset:128
	s_waitcnt lgkmcnt(0)
	v_mfma_f32_16x16x32_bf16 v[48:51], v[120:123], v[40:43], v[48:51]
	ds_read_b128 v[120:123], v105 offset:192
	s_waitcnt lgkmcnt(0)
	v_mfma_f32_16x16x32_bf16 v[48:51], v[120:123], v[44:47], v[48:51]
	ds_read2st64_b32 v[120:121], v119 offset1:4
	s_waitcnt lgkmcnt(0)
	s_nop 5
	v_fma_f32 v48, v63, v120, v48
	v_mul_f32_e32 v120, 0x3d372713, v48
	v_mul_f32_e32 v120, v48, v120
	v_fma_f32 v120, v48, v120, v48
	v_mul_f32_e32 v120, 0x3f4c422a, v120
	v_add_f32_e32 v120, v120, v120
	v_mul_f32_e32 v120, 0x3fb8aa3b, v120
	v_exp_f32_e32 v120, v120
	v_mul_f32_e32 v48, 0.5, v48
	v_fma_f32 v49, v63, v121, v49
	v_add_f32_e32 v120, 1.0, v120
	v_div_scale_f32 v122, s[14:15], v120, v120, 2.0
	v_rcp_f32_e32 v123, v122
	s_nop 0
	v_fma_f32 v124, -v122, v123, 1.0
	v_fmac_f32_e32 v123, v124, v123
	v_div_scale_f32 v124, vcc, 2.0, v120, 2.0
	v_mul_f32_e32 v125, v124, v123
	v_fma_f32 v126, -v122, v125, v124
	v_fmac_f32_e32 v125, v126, v123
	v_fma_f32 v122, -v122, v125, v124
	v_div_fmas_f32 v122, v122, v123, v125
	v_div_fixup_f32 v120, v122, v120, 2.0
	v_sub_f32_e32 v120, 1.0, v120
	v_add_f32_e32 v120, 1.0, v120
	v_mul_f32_e32 v48, v48, v120
	v_mul_f32_e32 v120, 0x3d372713, v49
	v_mul_f32_e32 v120, v49, v120
	v_fma_f32 v120, v49, v120, v49
	v_mul_f32_e32 v120, 0x3f4c422a, v120
	v_add_f32_e32 v120, v120, v120
	v_mul_f32_e32 v120, 0x3fb8aa3b, v120
	v_exp_f32_e32 v120, v120
	v_mul_f32_e32 v49, 0.5, v49
	v_add_f32_e32 v120, 1.0, v120
	v_div_scale_f32 v121, s[14:15], v120, v120, 2.0
	v_rcp_f32_e32 v122, v121
	s_nop 0
	v_fma_f32 v123, -v121, v122, 1.0
	v_fmac_f32_e32 v122, v123, v122
	v_div_scale_f32 v123, vcc, 2.0, v120, 2.0
	v_mul_f32_e32 v124, v123, v122
	v_fma_f32 v125, -v121, v124, v123
	v_fmac_f32_e32 v124, v125, v122
	v_fma_f32 v121, -v121, v124, v123
	v_div_fmas_f32 v121, v121, v122, v124
	v_div_fixup_f32 v120, v121, v120, 2.0
	v_sub_f32_e32 v120, 1.0, v120
	v_add_f32_e32 v120, 1.0, v120
	v_mul_f32_e32 v49, v49, v120
	ds_write2st64_b32 v119, v48, v49 offset1:4
	ds_read2st64_b32 v[48:49], v119 offset0:8 offset1:12
	s_waitcnt lgkmcnt(0)
	v_fma_f32 v48, v63, v48, v50
	v_mul_f32_e32 v50, 0x3d372713, v48
	v_mul_f32_e32 v50, v48, v50
	v_fma_f32 v50, v48, v50, v48
	v_mul_f32_e32 v50, 0x3f4c422a, v50
	v_add_f32_e32 v50, v50, v50
	v_mul_f32_e32 v50, 0x3fb8aa3b, v50
	v_exp_f32_e32 v50, v50
	v_fmac_f32_e32 v51, v63, v49
	v_mul_f32_e32 v49, 0x3d372713, v51
	v_mul_f32_e32 v49, v51, v49
	v_add_f32_e32 v50, 1.0, v50
	v_div_scale_f32 v120, s[14:15], v50, v50, 2.0
	v_rcp_f32_e32 v121, v120
	v_fma_f32 v49, v51, v49, v51
	v_mul_f32_e32 v49, 0x3f4c422a, v49
	v_add_f32_e32 v49, v49, v49
	v_fma_f32 v122, -v120, v121, 1.0
	v_fmac_f32_e32 v121, v122, v121
	v_div_scale_f32 v122, vcc, 2.0, v50, 2.0
	v_mul_f32_e32 v123, v122, v121
	v_fma_f32 v124, -v120, v123, v122
	v_fmac_f32_e32 v123, v124, v121
	v_mul_f32_e32 v49, 0x3fb8aa3b, v49
	v_fma_f32 v120, -v120, v123, v122
	v_exp_f32_e32 v49, v49
	v_div_fmas_f32 v120, v120, v121, v123
	v_div_fixup_f32 v50, v120, v50, 2.0
	v_sub_f32_e32 v50, 1.0, v50
	v_mul_f32_e32 v48, 0.5, v48
	v_add_f32_e32 v50, 1.0, v50
	v_add_f32_e32 v49, 1.0, v49
	v_mul_f32_e32 v48, v48, v50
	v_div_scale_f32 v50, s[14:15], v49, v49, 2.0
	v_rcp_f32_e32 v120, v50
	s_nop 0
	v_fma_f32 v121, -v50, v120, 1.0
	v_fmac_f32_e32 v120, v121, v120
	v_div_scale_f32 v121, vcc, 2.0, v49, 2.0
	v_mul_f32_e32 v122, v121, v120
	v_fma_f32 v123, -v50, v122, v121
	v_fmac_f32_e32 v122, v123, v120
	v_fma_f32 v50, -v50, v122, v121
	v_div_fmas_f32 v50, v50, v120, v122
	v_div_fixup_f32 v49, v50, v49, 2.0
	v_sub_f32_e32 v49, 1.0, v49
	v_mul_f32_e32 v50, 0.5, v51
	v_add_f32_e32 v49, 1.0, v49
	v_mul_f32_e32 v49, v50, v49
	ds_write2st64_b32 v119, v48, v49 offset0:8 offset1:12
	s_cbranch_scc0 .LBB0_496
	s_mov_b32 s1, 8
	s_mov_b64 s[56:57], 0
	s_and_b64 vcc, exec, s[12:13]
	s_cbranch_vccz .LBB0_475
	v_add_u32_e32 v0, v72, v99
	s_waitcnt lgkmcnt(0)
	s_barrier
	ds_read_b128 v[0:3], v0
	v_mov_b32_e32 v65, v161
	s_mov_b32 s1, 0x5000000
	s_add_i32 s40, s40, s34
	s_cmpk_gt_i32 s40, 0xff
	s_waitcnt lgkmcnt(0)
	v_cvt_pk_bf16_f32 v0, v0, v1
	v_cvt_pk_bf16_f32 v1, v2, v3
	ds_write_b64 v106, v[0:1]
	v_add_u32_e32 v0, v75, v99
	ds_read_b128 v[0:3], v0
	s_waitcnt lgkmcnt(0)
	v_cvt_pk_bf16_f32 v0, v0, v1
	v_cvt_pk_bf16_f32 v1, v2, v3
	ds_write_b64 v107, v[0:1]
	v_add_u32_e32 v0, v78, v99
	ds_read_b128 v[0:3], v0
	s_waitcnt lgkmcnt(0)
	v_cvt_pk_bf16_f32 v0, v0, v1
	v_cvt_pk_bf16_f32 v1, v2, v3
	ds_write_b64 v108, v[0:1]
	v_add_u32_e32 v0, v81, v99
	ds_read_b128 v[0:3], v0
	s_waitcnt lgkmcnt(0)
	v_cvt_pk_bf16_f32 v0, v0, v1
	v_cvt_pk_bf16_f32 v1, v2, v3
	ds_write_b64 v109, v[0:1]
	v_add_u32_e32 v0, v84, v99
	ds_read_b128 v[0:3], v0
	s_waitcnt lgkmcnt(0)
	v_cvt_pk_bf16_f32 v0, v0, v1
	v_cvt_pk_bf16_f32 v1, v2, v3
	ds_write_b64 v110, v[0:1]
	v_add_u32_e32 v0, v87, v99
	ds_read_b128 v[0:3], v0
	s_waitcnt lgkmcnt(0)
	v_cvt_pk_bf16_f32 v0, v0, v1
	v_cvt_pk_bf16_f32 v1, v2, v3
	ds_write_b64 v111, v[0:1]
	v_add_u32_e32 v0, v90, v99
	ds_read_b128 v[0:3], v0
	s_waitcnt lgkmcnt(0)
	v_cvt_pk_bf16_f32 v0, v0, v1
	v_cvt_pk_bf16_f32 v1, v2, v3
	ds_write_b64 v112, v[0:1]
	v_add_u32_e32 v0, v93, v99
	ds_read_b128 v[0:3], v0
	s_waitcnt lgkmcnt(0)
	v_cvt_pk_bf16_f32 v0, v0, v1
	v_cvt_pk_bf16_f32 v1, v2, v3
	ds_write_b64 v113, v[0:1]
	s_waitcnt lgkmcnt(0)
	s_barrier
	global_load_dwordx4 v[0:3], v[56:57], off
	global_load_dwordx4 v[4:7], v[58:59], off
	ds_read_b128 v[8:11], v114
	ds_read_b128 v[12:15], v114 offset:8448
	ds_read_b128 v[16:19], v114 offset:16896
	ds_read_b128 v[20:23], v114 offset:25344
	s_waitcnt vmcnt(1) lgkmcnt(3)
	v_mfma_f32_16x16x32_bf16 v[24:27], v[8:11], v[0:3], 0
	s_waitcnt vmcnt(0)
	v_mfma_f32_16x16x32_bf16 v[8:11], v[8:11], v[4:7], 0
	s_waitcnt lgkmcnt(2)
	v_mfma_f32_16x16x32_bf16 v[28:31], v[12:15], v[0:3], 0
	v_mfma_f32_16x16x32_bf16 v[12:15], v[12:15], v[4:7], 0
	s_waitcnt lgkmcnt(1)
	v_mfma_f32_16x16x32_bf16 v[32:35], v[16:19], v[0:3], 0
	v_mfma_f32_16x16x32_bf16 v[16:19], v[16:19], v[4:7], 0
	s_waitcnt lgkmcnt(0)
	v_mfma_f32_16x16x32_bf16 v[0:3], v[20:23], v[0:3], 0
	v_mfma_f32_16x16x32_bf16 v[4:7], v[20:23], v[4:7], 0
	global_load_dwordx4 v[20:23], v[56:57], off offset:64
	global_load_dwordx4 v[36:39], v[58:59], off offset:64
	ds_read_b128 v[40:43], v114 offset:64
	ds_read_b128 v[44:47], v114 offset:8512
	ds_read_b128 v[48:51], v114 offset:16960
	ds_read_b128 v[66:69], v114 offset:25408
	s_waitcnt vmcnt(1) lgkmcnt(3)
	v_mfma_f32_16x16x32_bf16 v[24:27], v[40:43], v[20:23], v[24:27]
	s_waitcnt vmcnt(0)
	v_mfma_f32_16x16x32_bf16 v[8:11], v[40:43], v[36:39], v[8:11]
	s_waitcnt lgkmcnt(2)
	v_mfma_f32_16x16x32_bf16 v[28:31], v[44:47], v[20:23], v[28:31]
	v_mfma_f32_16x16x32_bf16 v[12:15], v[44:47], v[36:39], v[12:15]
	s_waitcnt lgkmcnt(1)
	v_mfma_f32_16x16x32_bf16 v[32:35], v[48:51], v[20:23], v[32:35]
	v_mfma_f32_16x16x32_bf16 v[16:19], v[48:51], v[36:39], v[16:19]
	s_waitcnt lgkmcnt(0)
	v_mfma_f32_16x16x32_bf16 v[0:3], v[66:69], v[20:23], v[0:3]
	v_mfma_f32_16x16x32_bf16 v[4:7], v[66:69], v[36:39], v[4:7]
	global_load_dwordx4 v[20:23], v[56:57], off offset:128
	global_load_dwordx4 v[36:39], v[58:59], off offset:128
	ds_read_b128 v[40:43], v114 offset:128
	ds_read_b128 v[44:47], v114 offset:8576
	ds_read_b128 v[48:51], v114 offset:17024
	ds_read_b128 v[66:69], v114 offset:25472
	s_waitcnt vmcnt(1) lgkmcnt(3)
	v_mfma_f32_16x16x32_bf16 v[24:27], v[40:43], v[20:23], v[24:27]
	s_waitcnt vmcnt(0)
	v_mfma_f32_16x16x32_bf16 v[8:11], v[40:43], v[36:39], v[8:11]
	s_waitcnt lgkmcnt(2)
	v_mfma_f32_16x16x32_bf16 v[28:31], v[44:47], v[20:23], v[28:31]
	v_mfma_f32_16x16x32_bf16 v[12:15], v[44:47], v[36:39], v[12:15]
	s_waitcnt lgkmcnt(1)
	v_mfma_f32_16x16x32_bf16 v[32:35], v[48:51], v[20:23], v[32:35]
	v_mfma_f32_16x16x32_bf16 v[16:19], v[48:51], v[36:39], v[16:19]
	s_waitcnt lgkmcnt(0)
	v_mfma_f32_16x16x32_bf16 v[0:3], v[66:69], v[20:23], v[0:3]
	v_mfma_f32_16x16x32_bf16 v[4:7], v[66:69], v[36:39], v[4:7]
	global_load_dwordx4 v[20:23], v[56:57], off offset:192
	global_load_dwordx4 v[36:39], v[58:59], off offset:192
	ds_read_b128 v[40:43], v114 offset:192
	ds_read_b128 v[44:47], v114 offset:8640
	ds_read_b128 v[48:51], v114 offset:17088
	ds_read_b128 v[66:69], v114 offset:25536
	s_waitcnt vmcnt(1) lgkmcnt(3)
	v_mfma_f32_16x16x32_bf16 v[24:27], v[40:43], v[20:23], v[24:27]
	s_waitcnt vmcnt(0)
	v_mfma_f32_16x16x32_bf16 v[8:11], v[40:43], v[36:39], v[8:11]
	s_waitcnt lgkmcnt(2)
	v_mfma_f32_16x16x32_bf16 v[28:31], v[44:47], v[20:23], v[28:31]
	v_mfma_f32_16x16x32_bf16 v[12:15], v[44:47], v[36:39], v[12:15]
	s_waitcnt lgkmcnt(1)
	v_mfma_f32_16x16x32_bf16 v[32:35], v[48:51], v[20:23], v[32:35]
	v_mfma_f32_16x16x32_bf16 v[16:19], v[48:51], v[36:39], v[16:19]
	s_waitcnt lgkmcnt(0)
	v_mfma_f32_16x16x32_bf16 v[0:3], v[66:69], v[20:23], v[0:3]
	v_mfma_f32_16x16x32_bf16 v[4:7], v[66:69], v[36:39], v[4:7]
	global_load_dwordx4 v[20:23], v[56:57], off offset:256
	global_load_dwordx4 v[36:39], v[58:59], off offset:256
	ds_read_b128 v[40:43], v114 offset:256
	ds_read_b128 v[44:47], v114 offset:8704
	ds_read_b128 v[48:51], v114 offset:17152
	ds_read_b128 v[66:69], v114 offset:25600
	s_waitcnt vmcnt(1) lgkmcnt(3)
	v_mfma_f32_16x16x32_bf16 v[24:27], v[40:43], v[20:23], v[24:27]
	s_waitcnt vmcnt(0)
	v_mfma_f32_16x16x32_bf16 v[8:11], v[40:43], v[36:39], v[8:11]
	s_waitcnt lgkmcnt(2)
	v_mfma_f32_16x16x32_bf16 v[28:31], v[44:47], v[20:23], v[28:31]
	v_mfma_f32_16x16x32_bf16 v[12:15], v[44:47], v[36:39], v[12:15]
	s_waitcnt lgkmcnt(1)
	v_mfma_f32_16x16x32_bf16 v[32:35], v[48:51], v[20:23], v[32:35]
	v_mfma_f32_16x16x32_bf16 v[16:19], v[48:51], v[36:39], v[16:19]
	s_waitcnt lgkmcnt(0)
	v_mfma_f32_16x16x32_bf16 v[0:3], v[66:69], v[20:23], v[0:3]
	v_mfma_f32_16x16x32_bf16 v[4:7], v[66:69], v[36:39], v[4:7]
	global_load_dwordx4 v[20:23], v[56:57], off offset:320
	global_load_dwordx4 v[36:39], v[58:59], off offset:320
	ds_read_b128 v[40:43], v114 offset:320
	ds_read_b128 v[44:47], v114 offset:8768
	ds_read_b128 v[48:51], v114 offset:17216
	ds_read_b128 v[66:69], v114 offset:25664
	s_waitcnt vmcnt(1) lgkmcnt(3)
	v_mfma_f32_16x16x32_bf16 v[24:27], v[40:43], v[20:23], v[24:27]
	s_waitcnt vmcnt(0)
	v_mfma_f32_16x16x32_bf16 v[8:11], v[40:43], v[36:39], v[8:11]
	s_waitcnt lgkmcnt(2)
	v_mfma_f32_16x16x32_bf16 v[28:31], v[44:47], v[20:23], v[28:31]
	v_mfma_f32_16x16x32_bf16 v[12:15], v[44:47], v[36:39], v[12:15]
	s_waitcnt lgkmcnt(1)
	v_mfma_f32_16x16x32_bf16 v[32:35], v[48:51], v[20:23], v[32:35]
	v_mfma_f32_16x16x32_bf16 v[16:19], v[48:51], v[36:39], v[16:19]
	s_waitcnt lgkmcnt(0)
	v_mfma_f32_16x16x32_bf16 v[0:3], v[66:69], v[20:23], v[0:3]
	v_mfma_f32_16x16x32_bf16 v[4:7], v[66:69], v[36:39], v[4:7]
	global_load_dwordx4 v[20:23], v[56:57], off offset:384
	global_load_dwordx4 v[36:39], v[58:59], off offset:384
	ds_read_b128 v[40:43], v114 offset:384
	ds_read_b128 v[44:47], v114 offset:8832
	ds_read_b128 v[48:51], v114 offset:17280
	ds_read_b128 v[66:69], v114 offset:25728
	s_waitcnt vmcnt(1) lgkmcnt(3)
	v_mfma_f32_16x16x32_bf16 v[24:27], v[40:43], v[20:23], v[24:27]
	s_waitcnt vmcnt(0)
	v_mfma_f32_16x16x32_bf16 v[8:11], v[40:43], v[36:39], v[8:11]
	s_waitcnt lgkmcnt(2)
	v_mfma_f32_16x16x32_bf16 v[40:43], v[44:47], v[20:23], v[28:31]
	v_mfma_f32_16x16x32_bf16 v[12:15], v[44:47], v[36:39], v[12:15]
	s_waitcnt lgkmcnt(1)
	v_mfma_f32_16x16x32_bf16 v[32:35], v[48:51], v[20:23], v[32:35]
	v_mfma_f32_16x16x32_bf16 v[44:47], v[48:51], v[36:39], v[16:19]
	s_waitcnt lgkmcnt(0)
	v_mfma_f32_16x16x32_bf16 v[36:39], v[66:69], v[36:39], v[4:7]
	s_nop 2
	global_load_dwordx4 v[4:7], v[56:57], off offset:448
	global_load_dwordx4 v[48:51], v[58:59], off offset:448
	v_mfma_f32_16x16x32_bf16 v[0:3], v[66:69], v[20:23], v[0:3]
	ds_read_b128 v[16:19], v114 offset:448
	ds_read_b128 v[66:69], v114 offset:8896
	ds_read_b128 v[118:121], v114 offset:17344
	ds_read_b128 v[122:125], v114 offset:25792
	s_waitcnt vmcnt(1) lgkmcnt(3)
	v_mfma_f32_16x16x32_bf16 v[28:31], v[16:19], v[4:7], v[24:27]
	s_nop 7
	v_mul_f32_e32 v28, 0xbfb8aa3b, v28
	v_exp_f32_e32 v28, v28
	s_waitcnt vmcnt(0)
	v_mfma_f32_16x16x32_bf16 v[24:27], v[16:19], v[48:51], v[8:11]
	v_mul_f32_e32 v30, 0xbfb8aa3b, v30
	v_exp_f32_e32 v30, v30
	v_add_f32_e32 v28, 1.0, v28
	s_waitcnt lgkmcnt(2)
	v_mfma_f32_16x16x32_bf16 v[16:19], v[66:69], v[48:51], v[12:15]
	v_mul_f32_e32 v31, 0xbfb8aa3b, v31
	v_add_f32_e32 v30, 1.0, v30
	v_exp_f32_e32 v31, v31
	s_waitcnt lgkmcnt(1)
	v_mfma_f32_16x16x32_bf16 v[12:15], v[118:121], v[4:7], v[32:35]
	v_mul_f32_e32 v24, 0xbfb8aa3b, v24
	v_exp_f32_e32 v24, v24
	v_add_f32_e32 v31, 1.0, v31
	v_div_scale_f32 v34, s[12:13], v28, v28, 1.0
	v_rcp_f32_e32 v35, v34
	v_mfma_f32_16x16x32_bf16 v[20:23], v[66:69], v[4:7], v[40:43]
	ds_read2_b32 v[32:33], v115 offset1:16
	v_add_f32_e32 v24, 1.0, v24
	v_mul_f32_e32 v16, 0xbfb8aa3b, v16
	s_waitcnt lgkmcnt(1)
	v_mfma_f32_16x16x32_bf16 v[4:7], v[122:125], v[4:7], v[0:3]
	v_exp_f32_e32 v16, v16
	s_nop 1
	v_mul_f32_e32 v20, 0xbfb8aa3b, v20
	v_exp_f32_e32 v20, v20
	v_mfma_f32_16x16x32_bf16 v[0:3], v[122:125], v[48:51], v[36:39]
	v_mul_f32_e32 v22, 0xbfb8aa3b, v22
	v_exp_f32_e32 v22, v22
	v_add_f32_e32 v20, 1.0, v20
	v_fma_f32 v36, -v34, v35, 1.0
	v_fmac_f32_e32 v35, v36, v35
	v_div_scale_f32 v36, vcc, 1.0, v28, 1.0
	v_mul_f32_e32 v37, v36, v35
	v_fma_f32 v38, -v34, v37, v36
	v_fmac_f32_e32 v37, v38, v35
	v_fma_f32 v34, -v34, v37, v36
	v_div_fmas_f32 v34, v34, v35, v37
	v_div_fixup_f32 v28, v34, v28, 1.0
	s_waitcnt lgkmcnt(0)
	v_mul_f32_e32 v32, v28, v32
	v_mul_f32_e32 v28, 0xbfb8aa3b, v29
	v_exp_f32_e32 v28, v28
	v_add_u32_e32 v38, 0x400, v115
	ds_read2_b32 v[34:35], v38 offset1:16
	v_mfma_f32_16x16x32_bf16 v[8:11], v[118:121], v[48:51], v[44:47]
	v_add_f32_e32 v28, 1.0, v28
	v_div_scale_f32 v29, s[12:13], v28, v28, 1.0
	v_rcp_f32_e32 v36, v29
	v_add_f32_e32 v22, 1.0, v22
	v_mul_f32_e32 v23, 0xbfb8aa3b, v23
	v_exp_f32_e32 v23, v23
	v_fma_f32 v37, -v29, v36, 1.0
	v_fmac_f32_e32 v36, v37, v36
	v_div_scale_f32 v37, vcc, 1.0, v28, 1.0
	v_mul_f32_e32 v39, v37, v36
	v_fma_f32 v40, -v29, v39, v37
	v_fmac_f32_e32 v39, v40, v36
	v_fma_f32 v29, -v29, v39, v37
	v_div_fmas_f32 v29, v29, v36, v39
	v_div_scale_f32 v36, s[12:13], v30, v30, 1.0
	v_rcp_f32_e32 v37, v36
	v_div_fixup_f32 v28, v29, v28, 1.0
	v_add_u32_e32 v39, 0x800, v115
	s_waitcnt lgkmcnt(0)
	v_mul_f32_e32 v34, v28, v34
	v_fma_f32 v40, -v36, v37, 1.0
	v_fmac_f32_e32 v37, v40, v37
	v_div_scale_f32 v40, vcc, 1.0, v30, 1.0
	v_mul_f32_e32 v41, v40, v37
	v_fma_f32 v42, -v36, v41, v40
	v_fmac_f32_e32 v41, v42, v37
	v_fma_f32 v36, -v36, v41, v40
	v_div_scale_f32 v40, s[12:13], v31, v31, 1.0
	v_div_fmas_f32 v36, v36, v37, v41
	v_rcp_f32_e32 v41, v40
	ds_read2_b32 v[28:29], v39 offset1:16
	v_div_fixup_f32 v30, v36, v30, 1.0
	v_add_f32_e32 v23, 1.0, v23
	v_fma_f32 v42, -v40, v41, 1.0
	v_fmac_f32_e32 v41, v42, v41
	v_div_scale_f32 v42, vcc, 1.0, v31, 1.0
	s_waitcnt lgkmcnt(0)
	v_mul_f32_e32 v28, v30, v28
	v_add_u32_e32 v30, 0xc00, v115
	v_mul_f32_e32 v43, v42, v41
	ds_read2_b32 v[36:37], v30 offset1:16
	v_fma_f32 v44, -v40, v43, v42
	v_fmac_f32_e32 v43, v44, v41
	v_fma_f32 v40, -v40, v43, v42
	v_div_fmas_f32 v40, v40, v41, v43
	v_div_fixup_f32 v31, v40, v31, 1.0
	s_waitcnt lgkmcnt(0)
	v_mul_f32_e32 v31, v31, v36
	v_div_scale_f32 v36, s[12:13], v24, v24, 1.0
	v_rcp_f32_e32 v40, v36
	v_add_f32_e32 v16, 1.0, v16
	v_mul_f32_e32 v12, 0xbfb8aa3b, v12
	v_exp_f32_e32 v12, v12
	v_fma_f32 v41, -v36, v40, 1.0
	v_fmac_f32_e32 v40, v41, v40
	v_div_scale_f32 v41, vcc, 1.0, v24, 1.0
	v_mul_f32_e32 v42, v41, v40
	v_fma_f32 v43, -v36, v42, v41
	v_fmac_f32_e32 v42, v43, v40
	v_fma_f32 v36, -v36, v42, v41
	v_div_fmas_f32 v36, v36, v40, v42
	v_div_fixup_f32 v24, v36, v24, 1.0
	v_mul_f32_e32 v24, v24, v33
	ds_write2_b32 v115, v32, v24 offset1:16
	v_mul_f32_e32 v24, 0xbfb8aa3b, v25
	v_exp_f32_e32 v24, v24
	v_add_f32_e32 v12, 1.0, v12
	v_mul_f32_e32 v14, 0xbfb8aa3b, v14
	v_exp_f32_e32 v14, v14
	v_add_f32_e32 v24, 1.0, v24
	v_div_scale_f32 v25, s[12:13], v24, v24, 1.0
	v_rcp_f32_e32 v32, v25
	v_add_f32_e32 v14, 1.0, v14
	v_mul_f32_e32 v15, 0xbfb8aa3b, v15
	v_exp_f32_e32 v15, v15
	v_fma_f32 v33, -v25, v32, 1.0
	v_fmac_f32_e32 v32, v33, v32
	v_div_scale_f32 v33, vcc, 1.0, v24, 1.0
	v_mul_f32_e32 v36, v33, v32
	v_fma_f32 v40, -v25, v36, v33
	v_fmac_f32_e32 v36, v40, v32
	v_fma_f32 v25, -v25, v36, v33
	v_div_fmas_f32 v25, v25, v32, v36
	v_div_fixup_f32 v24, v25, v24, 1.0
	v_mul_f32_e32 v24, v24, v35
	ds_write2_b32 v38, v34, v24 offset1:16
	v_mul_f32_e32 v24, 0xbfb8aa3b, v26
	v_exp_f32_e32 v24, v24
	v_add_f32_e32 v15, 1.0, v15
	v_mul_f32_e32 v8, 0xbfb8aa3b, v8
	v_exp_f32_e32 v8, v8
	v_add_f32_e32 v24, 1.0, v24
	v_div_scale_f32 v25, s[12:13], v24, v24, 1.0
	v_rcp_f32_e32 v26, v25
	v_add_f32_e32 v8, 1.0, v8
	v_mul_f32_e32 v4, 0xbfb8aa3b, v4
	v_exp_f32_e32 v4, v4
	v_fma_f32 v32, -v25, v26, 1.0
	v_fmac_f32_e32 v26, v32, v26
	v_div_scale_f32 v32, vcc, 1.0, v24, 1.0
	v_mul_f32_e32 v33, v32, v26
	v_fma_f32 v34, -v25, v33, v32
	v_fmac_f32_e32 v33, v34, v26
	v_fma_f32 v25, -v25, v33, v32
	v_div_fmas_f32 v25, v25, v26, v33
	v_div_fixup_f32 v24, v25, v24, 1.0
	v_mul_f32_e32 v24, v24, v29
	ds_write2_b32 v39, v28, v24 offset1:16
	v_mul_f32_e32 v24, 0xbfb8aa3b, v27
	v_exp_f32_e32 v24, v24
	v_add_f32_e32 v4, 1.0, v4
	v_mul_f32_e32 v6, 0xbfb8aa3b, v6
	v_exp_f32_e32 v6, v6
	v_add_f32_e32 v24, 1.0, v24
	v_div_scale_f32 v25, s[12:13], v24, v24, 1.0
	v_rcp_f32_e32 v26, v25
	v_add_f32_e32 v6, 1.0, v6
	v_mul_f32_e32 v7, 0xbfb8aa3b, v7
	v_exp_f32_e32 v7, v7
	v_fma_f32 v27, -v25, v26, 1.0
	v_fmac_f32_e32 v26, v27, v26
	v_div_scale_f32 v27, vcc, 1.0, v24, 1.0
	v_mul_f32_e32 v28, v27, v26
	v_fma_f32 v29, -v25, v28, v27
	v_fmac_f32_e32 v28, v29, v26
	v_fma_f32 v25, -v25, v28, v27
	v_div_fmas_f32 v25, v25, v26, v28
	v_div_scale_f32 v26, s[12:13], v20, v20, 1.0
	v_rcp_f32_e32 v27, v26
	v_div_fixup_f32 v24, v25, v24, 1.0
	v_mul_f32_e32 v24, v24, v37
	ds_write2_b32 v30, v31, v24 offset1:16
	v_fma_f32 v28, -v26, v27, 1.0
	v_fmac_f32_e32 v27, v28, v27
	v_div_scale_f32 v28, vcc, 1.0, v20, 1.0
	v_add_u32_e32 v30, 0x4000, v115
	v_mul_f32_e32 v29, v28, v27
	ds_read2_b32 v[24:25], v30 offset1:16
	v_fma_f32 v31, -v26, v29, v28
	v_fmac_f32_e32 v29, v31, v27
	v_fma_f32 v26, -v26, v29, v28
	v_div_fmas_f32 v26, v26, v27, v29
	v_div_fixup_f32 v20, v26, v20, 1.0
	s_waitcnt lgkmcnt(0)
	v_mul_f32_e32 v24, v20, v24
	v_mul_f32_e32 v20, 0xbfb8aa3b, v21
	v_exp_f32_e32 v20, v20
	v_add_u32_e32 v31, 0x4400, v115
	ds_read2_b32 v[26:27], v31 offset1:16
	v_add_f32_e32 v7, 1.0, v7
	v_add_f32_e32 v20, 1.0, v20
	v_div_scale_f32 v21, s[12:13], v20, v20, 1.0
	v_rcp_f32_e32 v28, v21
	v_mul_f32_e32 v0, 0xbfb8aa3b, v0
	v_exp_f32_e32 v0, v0
	v_fma_f32 v29, -v21, v28, 1.0
	v_fmac_f32_e32 v28, v29, v28
	v_div_scale_f32 v29, vcc, 1.0, v20, 1.0
	v_mul_f32_e32 v32, v29, v28
	v_fma_f32 v33, -v21, v32, v29
	v_fmac_f32_e32 v32, v33, v28
	v_fma_f32 v21, -v21, v32, v29
	v_div_fmas_f32 v21, v21, v28, v32
	v_div_scale_f32 v28, s[12:13], v22, v22, 1.0
	v_rcp_f32_e32 v29, v28
	v_div_fixup_f32 v20, v21, v20, 1.0
	v_add_u32_e32 v32, 0x4800, v115
	s_waitcnt lgkmcnt(0)
	v_mul_f32_e32 v26, v20, v26
	v_fma_f32 v33, -v28, v29, 1.0
	v_fmac_f32_e32 v29, v33, v29
	v_div_scale_f32 v33, vcc, 1.0, v22, 1.0
	v_mul_f32_e32 v34, v33, v29
	v_fma_f32 v35, -v28, v34, v33
	v_fmac_f32_e32 v34, v35, v29
	v_fma_f32 v28, -v28, v34, v33
	v_div_scale_f32 v33, s[12:13], v23, v23, 1.0
	v_div_fmas_f32 v28, v28, v29, v34
	v_rcp_f32_e32 v34, v33
	ds_read2_b32 v[20:21], v32 offset1:16
	v_div_fixup_f32 v22, v28, v22, 1.0
	v_add_f32_e32 v0, 1.0, v0
	v_fma_f32 v35, -v33, v34, 1.0
	v_fmac_f32_e32 v34, v35, v34
	v_div_scale_f32 v35, vcc, 1.0, v23, 1.0
	s_waitcnt lgkmcnt(0)
	v_mul_f32_e32 v20, v22, v20
	v_add_u32_e32 v22, 0x4c00, v115
	v_mul_f32_e32 v36, v35, v34
	ds_read2_b32 v[28:29], v22 offset1:16
	v_fma_f32 v37, -v33, v36, v35
	v_fmac_f32_e32 v36, v37, v34
	v_fma_f32 v33, -v33, v36, v35
	v_div_fmas_f32 v33, v33, v34, v36
	v_div_fixup_f32 v23, v33, v23, 1.0
	s_waitcnt lgkmcnt(0)
	v_mul_f32_e32 v23, v23, v28
	v_div_scale_f32 v28, s[12:13], v16, v16, 1.0
	v_rcp_f32_e32 v33, v28
	s_nop 0
	v_fma_f32 v34, -v28, v33, 1.0
	v_fmac_f32_e32 v33, v34, v33
	v_div_scale_f32 v34, vcc, 1.0, v16, 1.0
	v_mul_f32_e32 v35, v34, v33
	v_fma_f32 v36, -v28, v35, v34
	v_fmac_f32_e32 v35, v36, v33
	v_fma_f32 v28, -v28, v35, v34
	v_div_fmas_f32 v28, v28, v33, v35
	v_div_fixup_f32 v16, v28, v16, 1.0
	v_mul_f32_e32 v16, v16, v25
	ds_write2_b32 v30, v24, v16 offset1:16
	v_mul_f32_e32 v16, 0xbfb8aa3b, v17
	v_exp_f32_e32 v16, v16
	s_nop 0
	v_add_f32_e32 v16, 1.0, v16
	v_div_scale_f32 v17, s[12:13], v16, v16, 1.0
	v_rcp_f32_e32 v24, v17
	s_nop 0
	v_fma_f32 v25, -v17, v24, 1.0
	v_fmac_f32_e32 v24, v25, v24
	v_div_scale_f32 v25, vcc, 1.0, v16, 1.0
	v_mul_f32_e32 v28, v25, v24
	v_fma_f32 v30, -v17, v28, v25
	v_fmac_f32_e32 v28, v30, v24
	v_fma_f32 v17, -v17, v28, v25
	v_div_fmas_f32 v17, v17, v24, v28
	v_div_fixup_f32 v16, v17, v16, 1.0
	v_mul_f32_e32 v16, v16, v27
	ds_write2_b32 v31, v26, v16 offset1:16
	v_mul_f32_e32 v16, 0xbfb8aa3b, v18
	v_exp_f32_e32 v16, v16
	s_nop 0
	v_add_f32_e32 v16, 1.0, v16
	v_div_scale_f32 v17, s[12:13], v16, v16, 1.0
	v_rcp_f32_e32 v18, v17
	s_nop 0
	v_fma_f32 v24, -v17, v18, 1.0
	v_fmac_f32_e32 v18, v24, v18
	v_div_scale_f32 v24, vcc, 1.0, v16, 1.0
	v_mul_f32_e32 v25, v24, v18
	v_fma_f32 v26, -v17, v25, v24
	v_fmac_f32_e32 v25, v26, v18
	v_fma_f32 v17, -v17, v25, v24
	v_div_fmas_f32 v17, v17, v18, v25
	v_div_fixup_f32 v16, v17, v16, 1.0
	v_mul_f32_e32 v16, v16, v21
	ds_write2_b32 v32, v20, v16 offset1:16
	v_mul_f32_e32 v16, 0xbfb8aa3b, v19
	v_exp_f32_e32 v16, v16
	s_nop 0
	v_add_f32_e32 v16, 1.0, v16
	v_div_scale_f32 v17, s[12:13], v16, v16, 1.0
	v_rcp_f32_e32 v18, v17
	s_nop 0
	v_fma_f32 v19, -v17, v18, 1.0
	v_fmac_f32_e32 v18, v19, v18
	v_div_scale_f32 v19, vcc, 1.0, v16, 1.0
	v_mul_f32_e32 v20, v19, v18
	v_fma_f32 v21, -v17, v20, v19
	v_fmac_f32_e32 v20, v21, v18
	v_fma_f32 v17, -v17, v20, v19
	v_div_fmas_f32 v17, v17, v18, v20
	v_div_scale_f32 v18, s[12:13], v12, v12, 1.0
	v_rcp_f32_e32 v19, v18
	v_div_fixup_f32 v16, v17, v16, 1.0
	v_mul_f32_e32 v16, v16, v29
	ds_write2_b32 v22, v23, v16 offset1:16
	v_fma_f32 v20, -v18, v19, 1.0
	v_fmac_f32_e32 v19, v20, v19
	v_div_scale_f32 v20, vcc, 1.0, v12, 1.0
	v_add_u32_e32 v22, 0x8000, v115
	v_mul_f32_e32 v21, v20, v19
	ds_read2_b32 v[16:17], v22 offset1:16
	v_fma_f32 v23, -v18, v21, v20
	v_fmac_f32_e32 v21, v23, v19
	v_fma_f32 v18, -v18, v21, v20
	v_div_fmas_f32 v18, v18, v19, v21
	v_div_fixup_f32 v12, v18, v12, 1.0
	s_waitcnt lgkmcnt(0)
	v_mul_f32_e32 v16, v12, v16
	v_mul_f32_e32 v12, 0xbfb8aa3b, v13
	v_exp_f32_e32 v12, v12
	v_add_u32_e32 v23, 0x8400, v115
	ds_read2_b32 v[18:19], v23 offset1:16
	v_add_f32_e32 v12, 1.0, v12
	v_div_scale_f32 v13, s[12:13], v12, v12, 1.0
	v_rcp_f32_e32 v20, v13
	s_nop 0
	v_fma_f32 v21, -v13, v20, 1.0
	v_fmac_f32_e32 v20, v21, v20
	v_div_scale_f32 v21, vcc, 1.0, v12, 1.0
	v_mul_f32_e32 v24, v21, v20
	v_fma_f32 v25, -v13, v24, v21
	v_fmac_f32_e32 v24, v25, v20
	v_fma_f32 v13, -v13, v24, v21
	v_div_fmas_f32 v13, v13, v20, v24
	v_div_scale_f32 v20, s[12:13], v14, v14, 1.0
	v_rcp_f32_e32 v21, v20
	v_div_fixup_f32 v12, v13, v12, 1.0
	v_add_u32_e32 v24, 0x8800, v115
	s_waitcnt lgkmcnt(0)
	v_mul_f32_e32 v18, v12, v18
	v_fma_f32 v25, -v20, v21, 1.0
	v_fmac_f32_e32 v21, v25, v21
	v_div_scale_f32 v25, vcc, 1.0, v14, 1.0
	v_mul_f32_e32 v26, v25, v21
	v_fma_f32 v27, -v20, v26, v25
	v_fmac_f32_e32 v26, v27, v21
	v_fma_f32 v20, -v20, v26, v25
	v_div_scale_f32 v25, s[12:13], v15, v15, 1.0
	v_div_fmas_f32 v20, v20, v21, v26
	v_rcp_f32_e32 v26, v25
	ds_read2_b32 v[12:13], v24 offset1:16
	v_div_fixup_f32 v14, v20, v14, 1.0
	v_fma_f32 v27, -v25, v26, 1.0
	v_fmac_f32_e32 v26, v27, v26
	v_div_scale_f32 v27, vcc, 1.0, v15, 1.0
	s_waitcnt lgkmcnt(0)
	v_mul_f32_e32 v12, v14, v12
	v_add_u32_e32 v14, 0x8c00, v115
	v_mul_f32_e32 v28, v27, v26
	ds_read2_b32 v[20:21], v14 offset1:16
	v_fma_f32 v29, -v25, v28, v27
	v_fmac_f32_e32 v28, v29, v26
	v_fma_f32 v25, -v25, v28, v27
	v_div_fmas_f32 v25, v25, v26, v28
	v_div_fixup_f32 v15, v25, v15, 1.0
	s_waitcnt lgkmcnt(0)
	v_mul_f32_e32 v15, v15, v20
	v_div_scale_f32 v20, s[12:13], v8, v8, 1.0
	v_rcp_f32_e32 v25, v20
	s_nop 0
	v_fma_f32 v26, -v20, v25, 1.0
	v_fmac_f32_e32 v25, v26, v25
	v_div_scale_f32 v26, vcc, 1.0, v8, 1.0
	v_mul_f32_e32 v27, v26, v25
	v_fma_f32 v28, -v20, v27, v26
	v_fmac_f32_e32 v27, v28, v25
	v_fma_f32 v20, -v20, v27, v26
	v_div_fmas_f32 v20, v20, v25, v27
	v_div_fixup_f32 v8, v20, v8, 1.0
	v_mul_f32_e32 v8, v8, v17
	ds_write2_b32 v22, v16, v8 offset1:16
	v_mul_f32_e32 v8, 0xbfb8aa3b, v9
	v_exp_f32_e32 v8, v8
	s_nop 0
	v_add_f32_e32 v8, 1.0, v8
	v_div_scale_f32 v9, s[12:13], v8, v8, 1.0
	v_rcp_f32_e32 v16, v9
	s_nop 0
	v_fma_f32 v17, -v9, v16, 1.0
	v_fmac_f32_e32 v16, v17, v16
	v_div_scale_f32 v17, vcc, 1.0, v8, 1.0
	v_mul_f32_e32 v20, v17, v16
	v_fma_f32 v22, -v9, v20, v17
	v_fmac_f32_e32 v20, v22, v16
	v_fma_f32 v9, -v9, v20, v17
	v_div_fmas_f32 v9, v9, v16, v20
	v_div_fixup_f32 v8, v9, v8, 1.0
	v_mul_f32_e32 v8, v8, v19
	ds_write2_b32 v23, v18, v8 offset1:16
	v_mul_f32_e32 v8, 0xbfb8aa3b, v10
	v_exp_f32_e32 v8, v8
	s_nop 0
	v_add_f32_e32 v8, 1.0, v8
	v_div_scale_f32 v9, s[12:13], v8, v8, 1.0
	v_rcp_f32_e32 v10, v9
	s_nop 0
	v_fma_f32 v16, -v9, v10, 1.0
	v_fmac_f32_e32 v10, v16, v10
	v_div_scale_f32 v16, vcc, 1.0, v8, 1.0
	v_mul_f32_e32 v17, v16, v10
	v_fma_f32 v18, -v9, v17, v16
	v_fmac_f32_e32 v17, v18, v10
	v_fma_f32 v9, -v9, v17, v16
	v_div_fmas_f32 v9, v9, v10, v17
	v_div_fixup_f32 v8, v9, v8, 1.0
	v_mul_f32_e32 v8, v8, v13
	ds_write2_b32 v24, v12, v8 offset1:16
	v_mul_f32_e32 v8, 0xbfb8aa3b, v11
	v_exp_f32_e32 v8, v8
	s_nop 0
	v_add_f32_e32 v8, 1.0, v8
	v_div_scale_f32 v9, s[12:13], v8, v8, 1.0
	v_rcp_f32_e32 v10, v9
	s_nop 0
	v_fma_f32 v11, -v9, v10, 1.0
	v_fmac_f32_e32 v10, v11, v10
	v_div_scale_f32 v11, vcc, 1.0, v8, 1.0
	v_mul_f32_e32 v12, v11, v10
	v_fma_f32 v13, -v9, v12, v11
	v_fmac_f32_e32 v12, v13, v10
	v_fma_f32 v9, -v9, v12, v11
	v_div_fmas_f32 v9, v9, v10, v12
	v_div_scale_f32 v10, s[12:13], v4, v4, 1.0
	v_rcp_f32_e32 v11, v10
	v_div_fixup_f32 v8, v9, v8, 1.0
	v_mul_f32_e32 v8, v8, v21
	ds_write2_b32 v14, v15, v8 offset1:16
	v_fma_f32 v12, -v10, v11, 1.0
	v_fmac_f32_e32 v11, v12, v11
	v_div_scale_f32 v12, vcc, 1.0, v4, 1.0
	v_add_u32_e32 v14, 0xc000, v115
	v_mul_f32_e32 v13, v12, v11
	ds_read2_b32 v[8:9], v14 offset1:16
	v_fma_f32 v15, -v10, v13, v12
	v_fmac_f32_e32 v13, v15, v11
	v_fma_f32 v10, -v10, v13, v12
	v_div_fmas_f32 v10, v10, v11, v13
	v_div_fixup_f32 v4, v10, v4, 1.0
	s_waitcnt lgkmcnt(0)
	v_mul_f32_e32 v8, v4, v8
	v_mul_f32_e32 v4, 0xbfb8aa3b, v5
	v_exp_f32_e32 v4, v4
	v_add_u32_e32 v15, 0xc400, v115
	ds_read2_b32 v[10:11], v15 offset1:16
	v_add_f32_e32 v4, 1.0, v4
	v_div_scale_f32 v5, s[12:13], v4, v4, 1.0
	v_rcp_f32_e32 v12, v5
	s_nop 0
	v_fma_f32 v13, -v5, v12, 1.0
	v_fmac_f32_e32 v12, v13, v12
	v_div_scale_f32 v13, vcc, 1.0, v4, 1.0
	v_mul_f32_e32 v16, v13, v12
	v_fma_f32 v17, -v5, v16, v13
	v_fmac_f32_e32 v16, v17, v12
	v_fma_f32 v5, -v5, v16, v13
	v_div_fmas_f32 v5, v5, v12, v16
	v_div_scale_f32 v12, s[12:13], v6, v6, 1.0
	v_rcp_f32_e32 v13, v12
	v_div_fixup_f32 v4, v5, v4, 1.0
	v_add_u32_e32 v16, 0xc800, v115
	s_waitcnt lgkmcnt(0)
	v_mul_f32_e32 v10, v4, v10
	v_fma_f32 v17, -v12, v13, 1.0
	v_fmac_f32_e32 v13, v17, v13
	v_div_scale_f32 v17, vcc, 1.0, v6, 1.0
	v_mul_f32_e32 v18, v17, v13
	v_fma_f32 v19, -v12, v18, v17
	v_fmac_f32_e32 v18, v19, v13
	v_fma_f32 v12, -v12, v18, v17
	v_div_scale_f32 v17, s[12:13], v7, v7, 1.0
	v_div_fmas_f32 v12, v12, v13, v18
	v_rcp_f32_e32 v18, v17
	ds_read2_b32 v[4:5], v16 offset1:16
	v_div_fixup_f32 v6, v12, v6, 1.0
	v_fma_f32 v19, -v17, v18, 1.0
	v_fmac_f32_e32 v18, v19, v18
	v_div_scale_f32 v19, vcc, 1.0, v7, 1.0
	s_waitcnt lgkmcnt(0)
	v_mul_f32_e32 v4, v6, v4
	v_add_u32_e32 v6, 0xcc00, v115
	v_mul_f32_e32 v20, v19, v18
	ds_read2_b32 v[12:13], v6 offset1:16
	v_fma_f32 v21, -v17, v20, v19
	v_fmac_f32_e32 v20, v21, v18
	v_fma_f32 v17, -v17, v20, v19
	v_div_fmas_f32 v17, v17, v18, v20
	v_div_fixup_f32 v7, v17, v7, 1.0
	s_waitcnt lgkmcnt(0)
	v_mul_f32_e32 v7, v7, v12
	v_div_scale_f32 v12, s[12:13], v0, v0, 1.0
	v_rcp_f32_e32 v17, v12
	s_nop 0
	v_fma_f32 v18, -v12, v17, 1.0
	v_fmac_f32_e32 v17, v18, v17
	v_div_scale_f32 v18, vcc, 1.0, v0, 1.0
	v_mul_f32_e32 v19, v18, v17
	v_fma_f32 v20, -v12, v19, v18
	v_fmac_f32_e32 v19, v20, v17
	v_fma_f32 v12, -v12, v19, v18
	v_div_fmas_f32 v12, v12, v17, v19
	v_div_fixup_f32 v0, v12, v0, 1.0
	v_mul_f32_e32 v0, v0, v9
	ds_write2_b32 v14, v8, v0 offset1:16
	v_mul_f32_e32 v0, 0xbfb8aa3b, v1
	v_exp_f32_e32 v0, v0
	s_nop 0
	v_add_f32_e32 v0, 1.0, v0
	v_div_scale_f32 v1, s[12:13], v0, v0, 1.0
	v_rcp_f32_e32 v8, v1
	s_nop 0
	v_fma_f32 v9, -v1, v8, 1.0
	v_fmac_f32_e32 v8, v9, v8
	v_div_scale_f32 v9, vcc, 1.0, v0, 1.0
	v_mul_f32_e32 v12, v9, v8
	v_fma_f32 v14, -v1, v12, v9
	v_fmac_f32_e32 v12, v14, v8
	v_fma_f32 v1, -v1, v12, v9
	v_div_fmas_f32 v1, v1, v8, v12
	v_div_fixup_f32 v0, v1, v0, 1.0
	v_mul_f32_e32 v0, v0, v11
	ds_write2_b32 v15, v10, v0 offset1:16
	v_mul_f32_e32 v0, 0xbfb8aa3b, v2
	v_exp_f32_e32 v0, v0
	s_nop 0
	v_add_f32_e32 v0, 1.0, v0
	v_div_scale_f32 v1, s[12:13], v0, v0, 1.0
	v_rcp_f32_e32 v2, v1
	s_nop 0
	v_fma_f32 v8, -v1, v2, 1.0
	v_fmac_f32_e32 v2, v8, v2
	v_div_scale_f32 v8, vcc, 1.0, v0, 1.0
	v_mul_f32_e32 v9, v8, v2
	v_fma_f32 v10, -v1, v9, v8
	v_fmac_f32_e32 v9, v10, v2
	v_fma_f32 v1, -v1, v9, v8
	v_div_fmas_f32 v1, v1, v2, v9
	v_div_fixup_f32 v0, v1, v0, 1.0
	v_mul_f32_e32 v0, v0, v5
	ds_write2_b32 v16, v4, v0 offset1:16
	v_mul_f32_e32 v0, 0xbfb8aa3b, v3
	v_exp_f32_e32 v0, v0
	s_nop 0
	v_add_f32_e32 v0, 1.0, v0
	v_div_scale_f32 v1, s[12:13], v0, v0, 1.0
	v_rcp_f32_e32 v2, v1
	s_nop 0
	v_fma_f32 v3, -v1, v2, 1.0
	v_fmac_f32_e32 v2, v3, v2
	v_div_scale_f32 v3, vcc, 1.0, v0, 1.0
	v_mul_f32_e32 v4, v3, v2
	v_fma_f32 v5, -v1, v4, v3
	v_fmac_f32_e32 v4, v5, v2
	v_fma_f32 v1, -v1, v4, v3
	v_div_fmas_f32 v1, v1, v2, v4
	v_div_fixup_f32 v0, v1, v0, 1.0
	v_mul_f32_e32 v0, v0, v13
	ds_write2_b32 v6, v7, v0 offset1:16
	s_waitcnt lgkmcnt(0)
	s_barrier
	ds_read_b128 v[24:27], v116
	ds_read_b128 v[20:23], v116 offset:16
	ds_read_b128 v[4:7], v116 offset:32
	ds_read_b128 v[0:3], v116 offset:48
	ds_read_b128 v[28:31], v116 offset:80
	s_waitcnt lgkmcnt(4)
	v_mov_b32_e32 v10, v25
	s_waitcnt lgkmcnt(3)
	v_mov_b32_e32 v11, v21
	v_mov_b32_e32 v8, v24
	v_mov_b32_e32 v9, v20
	v_pk_mul_f32 v[10:11], v[10:11], v[10:11]
	v_mov_b32_e32 v12, v27
	v_mov_b32_e32 v13, v23
	v_pk_fma_f32 v[8:9], v[8:9], v[8:9], v[10:11]
	v_mov_b32_e32 v10, v26
	v_mov_b32_e32 v11, v22
	v_pk_mul_f32 v[12:13], v[12:13], v[12:13]
	s_nop 0
	v_pk_fma_f32 v[10:11], v[10:11], v[10:11], v[12:13]
	s_nop 0
	v_pk_add_f32 v[12:13], v[8:9], v[10:11]
	s_waitcnt lgkmcnt(2)
	v_pk_mul_f32 v[8:9], v[6:7], v[6:7]
	v_pk_mul_f32 v[10:11], v[4:5], v[4:5]
	v_pk_add_f32 v[12:13], v[12:13], v[12:13] op_sel:[0,1] op_sel_hi:[1,0]
	v_pk_mov_b32 v[14:15], v[10:11], v[8:9] op_sel:[1,0]
	v_mov_b32_e32 v11, v9
	v_pk_add_f32 v[14:15], v[14:15], v[10:11]
	ds_read_b128 v[8:11], v116 offset:64
	v_pk_add_f32 v[14:15], v[14:15], v[14:15] op_sel:[0,1] op_sel_hi:[1,0]
	s_waitcnt lgkmcnt(0)
	v_mul_f32_e32 v16, v8, v8
	v_mul_f32_e32 v17, v9, v9
	v_mov_b32_e32 v13, v16
	v_mov_b32_e32 v15, v17
	v_pk_add_f32 v[12:13], v[12:13], v[14:15]
	v_mul_f32_e32 v14, v1, v1
	v_mul_f32_e32 v16, v3, v3
	v_mul_f32_e32 v18, v10, v10
	v_mul_f32_e32 v19, v11, v11
	v_pk_fma_f32 v[14:15], v[0:1], v[0:1], v[14:15] op_sel_hi:[1,1,0]
	v_pk_fma_f32 v[16:17], v[2:3], v[2:3], v[16:17] op_sel_hi:[1,1,0]
	v_mov_b32_e32 v15, v18
	v_mov_b32_e32 v17, v19
	v_pk_add_f32 v[14:15], v[14:15], v[16:17]
	s_nop 0
	v_pk_add_f32 v[32:33], v[12:13], v[14:15]
	v_pk_mul_f32 v[12:13], v[30:31], v[30:31]
	v_pk_mul_f32 v[14:15], v[28:29], v[28:29]
	v_pk_add_f32 v[32:33], v[32:33], v[32:33] op_sel:[0,1] op_sel_hi:[1,0]
	v_pk_mov_b32 v[16:17], v[14:15], v[12:13] op_sel:[1,0]
	v_mov_b32_e32 v15, v13
	v_pk_add_f32 v[34:35], v[16:17], v[14:15]
	ds_read_b128 v[16:19], v116 offset:96
	ds_read_b128 v[12:15], v116 offset:112
	v_pk_add_f32 v[34:35], v[34:35], v[34:35] op_sel:[0,1] op_sel_hi:[1,0]
	s_waitcnt lgkmcnt(0)
	v_mul_f32_e32 v36, v12, v12
	v_mul_f32_e32 v37, v13, v13
	v_mov_b32_e32 v33, v36
	v_mov_b32_e32 v35, v37
	v_pk_add_f32 v[32:33], v[32:33], v[34:35]
	v_mul_f32_e32 v34, v17, v17
	v_mul_f32_e32 v36, v19, v19
	v_mul_f32_e32 v38, v14, v14
	v_mul_f32_e32 v39, v15, v15
	v_pk_fma_f32 v[34:35], v[16:17], v[16:17], v[34:35] op_sel_hi:[1,1,0]
	v_pk_fma_f32 v[36:37], v[18:19], v[18:19], v[36:37] op_sel_hi:[1,1,0]
	v_mov_b32_e32 v35, v38
	v_mov_b32_e32 v37, v39
	v_pk_add_f32 v[34:35], v[34:35], v[36:37]
	s_nop 0
	v_pk_add_f32 v[32:33], v[32:33], v[34:35]
	s_nop 0
	v_add_f32_e32 v32, v32, v33
	s_nop 1
	v_add_f32_dpp v32, v32, v32 quad_perm:[1,0,3,2] row_mask:0xf bank_mask:0xf bound_ctrl:1
	s_nop 1
	v_add_f32_dpp v32, v32, v32 quad_perm:[2,3,0,1] row_mask:0xf bank_mask:0xf bound_ctrl:1
	s_nop 1
	v_add_f32_dpp v32, v32, v32 row_half_mirror row_mask:0xf bank_mask:0xf bound_ctrl:1
	v_fmamk_f32 v32, v32, 0x3b800000, v182
	v_cmp_gt_f32_e32 vcc, s50, v32
	v_mul_f32_e32 v33, 0x4f800000, v32
	s_nop 0
	v_cndmask_b32_e32 v32, v32, v33, vcc
	v_sqrt_f32_e32 v33, v32
	s_nop 0
	v_add_u32_e32 v34, -1, v33
	v_fma_f32 v35, -v34, v33, v32
	v_cmp_ge_f32_e64 s[12:13], 0, v35
	v_add_u32_e32 v35, 1, v33
	s_nop 0
	v_cndmask_b32_e64 v34, v33, v34, s[12:13]
	v_fma_f32 v33, -v35, v33, v32
	v_cmp_lt_f32_e64 s[12:13], 0, v33
	s_nop 1
	v_cndmask_b32_e64 v33, v34, v35, s[12:13]
	v_mul_f32_e32 v34, 0x37800000, v33
	v_cndmask_b32_e32 v33, v33, v34, vcc
	v_cmp_class_f32_e32 vcc, v32, v183
	s_nop 1
	v_cndmask_b32_e32 v32, v33, v32, vcc
	v_div_scale_f32 v33, s[12:13], v32, v32, 1.0
	v_rcp_f32_e32 v34, v33
	s_mov_b64 s[12:13], 0x5000200
	v_fma_f32 v35, -v33, v34, 1.0
	v_fmac_f32_e32 v34, v35, v34
	v_div_scale_f32 v35, vcc, 1.0, v32, 1.0
	v_mul_f32_e32 v36, v35, v34
	v_fma_f32 v37, -v33, v36, v35
	v_fmac_f32_e32 v36, v37, v34
	v_fma_f32 v33, -v33, v36, v35
	v_div_fmas_f32 v33, v33, v34, v36
	v_div_fixup_f32 v40, v33, v32, 1.0
	v_add_u32_e32 v32, s52, v100
	v_ashrrev_i32_e32 v33, 31, v32
	v_lshlrev_b64 v[32:33], 11, v[32:33]
	v_lshl_add_u64 v[32:33], s[18:19], 0, v[32:33]
	v_lshl_add_u64 v[44:45], v[32:33], 0, v[64:65]
	global_load_dwordx4 v[32:35], v[60:61], off offset:16
	global_load_dwordx4 v[36:39], v[60:61], off
	v_pk_mul_f32 v[24:25], v[24:25], v[40:41] op_sel_hi:[1,0]
	v_pk_mul_f32 v[26:27], v[26:27], v[40:41] op_sel_hi:[1,0]
	v_pk_mul_f32 v[20:21], v[20:21], v[40:41] op_sel_hi:[1,0]
	v_pk_mul_f32 v[4:5], v[4:5], v[40:41] op_sel_hi:[1,0]
	v_pk_mul_f32 v[6:7], v[6:7], v[40:41] op_sel_hi:[1,0]
	v_pk_mul_f32 v[0:1], v[0:1], v[40:41] op_sel_hi:[1,0]
	v_lshl_add_u64 v[42:43], v[44:45], 0, s[12:13]
	v_pk_mul_f32 v[8:9], v[8:9], v[40:41] op_sel_hi:[1,0]
	s_waitcnt vmcnt(1)
	v_pk_mul_f32 v[20:21], v[32:33], v[20:21]
	s_waitcnt vmcnt(0)
	v_pk_mul_f32 v[24:25], v[36:37], v[24:25]
	v_pk_mul_f32 v[26:27], v[38:39], v[26:27]
	v_cvt_pk_bf16_f32 v24, v24, v25
	v_cvt_pk_bf16_f32 v25, v26, v27
	v_cvt_pk_bf16_f32 v26, v20, v21
	v_pk_mul_f32 v[20:21], v[22:23], v[40:41] op_sel_hi:[1,0]
	s_nop 0
	v_pk_mul_f32 v[20:21], v[34:35], v[20:21]
	s_nop 0
	v_cvt_pk_bf16_f32 v27, v20, v21
	v_add_co_u32_e32 v20, vcc, s1, v44
	s_nop 1
	v_addc_co_u32_e32 v21, vcc, 0, v45, vcc
	global_store_dwordx4 v[20:21], v[24:27], off offset:512
	global_load_dwordx4 v[20:23], v[60:61], off offset:48
	s_nop 0
	global_load_dwordx4 v[24:27], v[60:61], off offset:32
	s_waitcnt vmcnt(1)
	v_pk_mul_f32 v[0:1], v[0:1], v[20:21]
	s_waitcnt vmcnt(0)
	v_pk_mul_f32 v[4:5], v[4:5], v[24:25]
	v_pk_mul_f32 v[6:7], v[6:7], v[26:27]
	v_cvt_pk_bf16_f32 v4, v4, v5
	v_cvt_pk_bf16_f32 v5, v6, v7
	v_cvt_pk_bf16_f32 v6, v0, v1
	v_pk_mul_f32 v[0:1], v[2:3], v[40:41] op_sel_hi:[1,0]
	s_nop 0
	v_pk_mul_f32 v[0:1], v[0:1], v[22:23]
	s_nop 0
	v_cvt_pk_bf16_f32 v7, v0, v1
	global_store_dwordx4 v[42:43], v[4:7], off offset:16
	global_load_dwordx4 v[0:3], v[60:61], off offset:80
	s_nop 0
	global_load_dwordx4 v[4:7], v[60:61], off offset:64
	s_waitcnt vmcnt(0)
	v_pk_mul_f32 v[4:5], v[8:9], v[4:5]
	v_pk_mul_f32 v[8:9], v[10:11], v[40:41] op_sel_hi:[1,0]
	v_cvt_pk_bf16_f32 v4, v4, v5
	v_pk_mul_f32 v[6:7], v[8:9], v[6:7]
	v_pk_mul_f32 v[8:9], v[16:17], v[40:41] op_sel_hi:[1,0]
	v_cvt_pk_bf16_f32 v5, v6, v7
	v_pk_mul_f32 v[6:7], v[28:29], v[40:41] op_sel_hi:[1,0]
	s_nop 0
	v_pk_mul_f32 v[0:1], v[6:7], v[0:1]
	s_nop 0
	v_cvt_pk_bf16_f32 v6, v0, v1
	v_pk_mul_f32 v[0:1], v[30:31], v[40:41] op_sel_hi:[1,0]
	s_nop 0
	v_pk_mul_f32 v[0:1], v[0:1], v[2:3]
	s_nop 0
	v_cvt_pk_bf16_f32 v7, v0, v1
	global_store_dwordx4 v[42:43], v[4:7], off offset:32
	global_load_dwordx4 v[0:3], v[60:61], off offset:112
	s_nop 0
	global_load_dwordx4 v[4:7], v[60:61], off offset:96
	s_waitcnt vmcnt(0)
	v_pk_mul_f32 v[4:5], v[8:9], v[4:5]
	v_pk_mul_f32 v[8:9], v[18:19], v[40:41] op_sel_hi:[1,0]
	v_cvt_pk_bf16_f32 v4, v4, v5
	v_pk_mul_f32 v[6:7], v[8:9], v[6:7]
	s_nop 0
	v_cvt_pk_bf16_f32 v5, v6, v7
	v_pk_mul_f32 v[6:7], v[12:13], v[40:41] op_sel_hi:[1,0]
	s_nop 0
	v_pk_mul_f32 v[0:1], v[6:7], v[0:1]
	s_nop 0
	v_cvt_pk_bf16_f32 v6, v0, v1
	v_pk_mul_f32 v[0:1], v[14:15], v[40:41] op_sel_hi:[1,0]
	s_nop 0
	v_pk_mul_f32 v[0:1], v[0:1], v[2:3]
	s_nop 0
	v_cvt_pk_bf16_f32 v7, v0, v1
	global_store_dwordx4 v[42:43], v[4:7], off offset:48
	s_barrier
	s_cbranch_scc0 .LBB0_474
	v_readlane_b32 s38, v254, 59
	v_readlane_b32 s39, v254, 60
